# FF2 epilogue: counted waits at the first consumer of each residual load instead of one vmcnt(0) after all 16 (asm guide 7.2)
# speedup vs baseline: 1.0087x; 1.0087x over previous
;     __device__ __forceinline__ void operator()(const f32x4 (&acc)[2][2][4][2], const pg8::Unit& u, int wr, int wc, int fr, int fq) const {
;         u32x4 xr[2][4][2];
; #pragma unroll
;         for (int ai = 0; ai < 2; ++ai)
; #pragma unroll
;             for (int m = 0; m < 4; ++m)
; #pragma unroll
;                 for (int bj = 0; bj < 2; ++bj)
;                     xr[ai][m][bj] = *(const u32x4*)(x2b + (size_t)(u.pm * 256 + ai * 128 + wr * 64 + m * 16 + fr) * DM + u.pn * 256 + 128 * bj + 32 * wc + 8 * fq);
;         __builtin_amdgcn_sched_barrier(0);
; #pragma unroll
;         for (int ai = 0; ai < 2; ++ai)
; #pragma unroll
;             for (int m = 0; m < 4; ++m) {
;                 const int row = u.pm * 256 + ai * 128 + wr * 64 + m * 16 + fr;
; #pragma unroll
;                 for (int bj = 0; bj < 2; ++bj) {
;                     const size_t off = (size_t)row * DM + u.pn * 256 + 128 * bj + 32 * wc + 8 * fq;
;                     const u32x4 w = xr[ai][m][bj];
;                     f32x4 ya = acc[ai][bj][m][0], yb = acc[ai][bj][m][1];
;                     ya.x += __uint_as_float(w.x << 16); ya.y += __uint_as_float(w.x & 0xffff0000u); ya.z += __uint_as_float(w.y << 16); ya.w += __uint_as_float(w.y & 0xffff0000u);
;                     yb.x += __uint_as_float(w.z << 16); yb.y += __uint_as_float(w.z & 0xffff0000u); yb.z += __uint_as_float(w.w << 16); yb.w += __uint_as_float(w.w & 0xffff0000u);
;                     *(f32x4*)(out + off) = ya; *(f32x4*)(out + off + 4) = yb;
.LBB0_1064:
	v_lshl_add_u32 v226, s16, 8, v179
	s_lshl_b32 s18, s40, 8
	s_ashr_i32 s19, s18, 31
	v_ashrrev_i32_e32 v227, 31, v226
	v_lshl_add_u64 v[128:129], s[18:19], 1, v[176:177]
	v_lshlrev_b64 v[130:131], 11, v[226:227]
	v_or_b32_e32 v228, 16, v226
	v_lshl_add_u64 v[130:131], v[128:129], 0, v[130:131]
	v_ashrrev_i32_e32 v229, 31, v228
	global_load_dwordx4 v[202:205], v[130:131], off nt
	global_load_dwordx4 v[206:209], v[130:131], off offset:256 nt
	v_lshlrev_b64 v[130:131], 11, v[228:229]
	v_or_b32_e32 v230, 32, v226
	v_lshl_add_u64 v[130:131], v[128:129], 0, v[130:131]
	v_ashrrev_i32_e32 v231, 31, v230
	global_load_dwordx4 v[210:213], v[130:131], off nt
	global_load_dwordx4 v[214:217], v[130:131], off offset:256 nt
	v_lshlrev_b64 v[130:131], 11, v[230:231]
	v_or_b32_e32 v196, 48, v226
	v_lshl_add_u64 v[130:131], v[128:129], 0, v[130:131]
	v_ashrrev_i32_e32 v197, 31, v196
	global_load_dwordx4 v[218:221], v[130:131], off nt
	global_load_dwordx4 v[222:225], v[130:131], off offset:256 nt
	v_lshlrev_b64 v[130:131], 11, v[196:197]
	v_add_u32_e32 v194, 0x80, v226
	v_lshl_add_u64 v[130:131], v[128:129], 0, v[130:131]
	v_ashrrev_i32_e32 v195, 31, v194
	global_load_dwordx4 v[164:167], v[130:131], off nt
	global_load_dwordx4 v[160:163], v[130:131], off offset:256 nt
	v_lshlrev_b64 v[130:131], 11, v[194:195]
	v_add_u32_e32 v192, 0x90, v226
	v_lshl_add_u64 v[130:131], v[128:129], 0, v[130:131]
	v_ashrrev_i32_e32 v193, 31, v192
	global_load_dwordx4 v[156:159], v[130:131], off nt
	global_load_dwordx4 v[152:155], v[130:131], off offset:256 nt
	v_lshlrev_b64 v[130:131], 11, v[192:193]
	v_add_u32_e32 v190, 0xa0, v226
	v_lshl_add_u64 v[130:131], v[128:129], 0, v[130:131]
	v_ashrrev_i32_e32 v191, 31, v190
	global_load_dwordx4 v[148:151], v[130:131], off nt
	global_load_dwordx4 v[144:147], v[130:131], off offset:256 nt
	v_lshlrev_b64 v[130:131], 11, v[190:191]
	v_add_u32_e32 v188, 0xb0, v226
	v_lshl_add_u64 v[130:131], v[128:129], 0, v[130:131]
	v_ashrrev_i32_e32 v189, 31, v188
	global_load_dwordx4 v[140:143], v[130:131], off nt
	global_load_dwordx4 v[136:139], v[130:131], off offset:256 nt
	v_lshlrev_b64 v[130:131], 11, v[188:189]
	v_lshl_add_u64 v[128:129], v[128:129], 0, v[130:131]
	global_load_dwordx4 v[132:135], v[128:129], off nt
	s_nop 0
	global_load_dwordx4 v[128:131], v[128:129], off offset:256 nt
	s_waitcnt vmcnt(15)
	v_lshlrev_b32_e32 v234, 16, v202
	v_and_b32_e32 v235, 0xffff0000, v202
	v_lshlrev_b32_e32 v202, 16, v203
	v_and_b32_e32 v203, 0xffff0000, v203
	v_pk_add_f32 v[126:127], v[126:127], v[202:203]
	v_lshlrev_b32_e32 v202, 16, v204
	v_and_b32_e32 v203, 0xffff0000, v204
	v_pk_add_f32 v[202:203], v[120:121], v[202:203]
	v_lshlrev_b32_e32 v120, 16, v205
	v_and_b32_e32 v121, 0xffff0000, v205
	v_mov_b32_e32 v233, s19
	v_or_b32_e32 v232, s18, v178
	v_pk_add_f32 v[204:205], v[122:123], v[120:121]
	v_lshlrev_b64 v[120:121], 12, v[226:227]
	v_lshl_add_u64 v[122:123], s[76:77], 0, v[120:121]
	v_lshlrev_b64 v[120:121], 2, v[232:233]
	v_pk_add_f32 v[124:125], v[124:125], v[234:235]
	v_lshl_add_u64 v[122:123], v[122:123], 0, v[120:121]
	global_store_dwordx4 v[122:123], v[124:127], off nt
	global_store_dwordx4 v[122:123], v[202:205], off offset:16 nt
	s_andn2_b64 vcc, exec, s[0:1]
	s_waitcnt vmcnt(14)
	v_lshlrev_b32_e32 v124, 16, v206
	v_and_b32_e32 v125, 0xffff0000, v206
	v_pk_add_f32 v[116:117], v[116:117], v[124:125]
	v_lshlrev_b32_e32 v124, 16, v207
	v_and_b32_e32 v125, 0xffff0000, v207
	v_pk_add_f32 v[118:119], v[118:119], v[124:125]
	v_lshlrev_b32_e32 v124, 16, v208
	v_and_b32_e32 v125, 0xffff0000, v208
	v_pk_add_f32 v[108:109], v[108:109], v[124:125]
	v_lshlrev_b32_e32 v124, 16, v209
	v_and_b32_e32 v125, 0xffff0000, v209
	v_pk_add_f32 v[110:111], v[110:111], v[124:125]
	global_store_dwordx4 v[122:123], v[116:119], off offset:512 nt
	global_store_dwordx4 v[122:123], v[108:111], off offset:528 nt
	s_mov_b64 s[0:1], -1
	s_nop 0
	s_waitcnt vmcnt(13)
	v_lshlrev_b32_e32 v108, 16, v210
	v_and_b32_e32 v109, 0xffff0000, v210
	v_pk_add_f32 v[108:109], v[112:113], v[108:109]
	v_lshlrev_b32_e32 v112, 16, v212
	v_and_b32_e32 v113, 0xffff0000, v212
	v_pk_add_f32 v[104:105], v[104:105], v[112:113]
	v_lshlrev_b32_e32 v112, 16, v213
	v_and_b32_e32 v113, 0xffff0000, v213
	v_pk_add_f32 v[106:107], v[106:107], v[112:113]
	v_lshlrev_b64 v[112:113], 12, v[228:229]
	v_lshlrev_b32_e32 v110, 16, v211
	v_and_b32_e32 v111, 0xffff0000, v211
	v_lshl_add_u64 v[112:113], s[76:77], 0, v[112:113]
	v_pk_add_f32 v[110:111], v[114:115], v[110:111]
	v_lshl_add_u64 v[112:113], v[112:113], 0, v[120:121]
	global_store_dwordx4 v[112:113], v[108:111], off nt
	global_store_dwordx4 v[112:113], v[104:107], off offset:16 nt
	s_nop 1
	s_waitcnt vmcnt(12)
	v_lshlrev_b32_e32 v104, 16, v214
	v_and_b32_e32 v105, 0xffff0000, v214
	v_pk_add_f32 v[100:101], v[100:101], v[104:105]
	v_lshlrev_b32_e32 v104, 16, v215
	v_and_b32_e32 v105, 0xffff0000, v215
	v_pk_add_f32 v[102:103], v[102:103], v[104:105]
	v_lshlrev_b32_e32 v104, 16, v216
	v_and_b32_e32 v105, 0xffff0000, v216
	v_pk_add_f32 v[92:93], v[92:93], v[104:105]
	v_lshlrev_b32_e32 v104, 16, v217
	v_and_b32_e32 v105, 0xffff0000, v217
	v_pk_add_f32 v[94:95], v[94:95], v[104:105]
	global_store_dwordx4 v[112:113], v[100:103], off offset:512 nt
	global_store_dwordx4 v[112:113], v[92:95], off offset:528 nt
	s_nop 1
	s_waitcnt vmcnt(11)
;     __device__ __forceinline__ void operator()(const f32x4 (&acc)[2][2][4][2], const pg8::Unit& u, int wr, int wc, int fr, int fq) const {
;     ...
;         for (int ai = 0; ai < 2; ++ai)
; #pragma unroll
;             for (int m = 0; m < 4; ++m) {
;                 const int row = u.pm * 256 + ai * 128 + wr * 64 + m * 16 + fr;
; #pragma unroll
;                 for (int bj = 0; bj < 2; ++bj) {
;                     const size_t off = (size_t)row * DM + u.pn * 256 + 128 * bj + 32 * wc + 8 * fq;
;                     const u32x4 w = xr[ai][m][bj];
;                     f32x4 ya = acc[ai][bj][m][0], yb = acc[ai][bj][m][1];
;                     ya.x += __uint_as_float(w.x << 16); ya.y += __uint_as_float(w.x & 0xffff0000u); ya.z += __uint_as_float(w.y << 16); ya.w += __uint_as_float(w.y & 0xffff0000u);
;                     yb.x += __uint_as_float(w.z << 16); yb.y += __uint_as_float(w.z & 0xffff0000u); yb.z += __uint_as_float(w.w << 16); yb.w += __uint_as_float(w.w & 0xffff0000u);
;                     *(f32x4*)(out + off) = ya; *(f32x4*)(out + off + 4) = yb;
;                 }
	v_lshlrev_b32_e32 v92, 16, v218
	v_and_b32_e32 v93, 0xffff0000, v218
	v_pk_add_f32 v[92:93], v[96:97], v[92:93]
	v_lshlrev_b32_e32 v96, 16, v220
	v_and_b32_e32 v97, 0xffff0000, v220
	v_pk_add_f32 v[88:89], v[88:89], v[96:97]
	v_lshlrev_b32_e32 v96, 16, v221
	v_and_b32_e32 v97, 0xffff0000, v221
	v_pk_add_f32 v[90:91], v[90:91], v[96:97]
	v_lshlrev_b64 v[96:97], 12, v[230:231]
	v_lshlrev_b32_e32 v94, 16, v219
	v_and_b32_e32 v95, 0xffff0000, v219
	v_lshl_add_u64 v[96:97], s[76:77], 0, v[96:97]
	v_pk_add_f32 v[94:95], v[98:99], v[94:95]
	v_lshl_add_u64 v[96:97], v[96:97], 0, v[120:121]
	global_store_dwordx4 v[96:97], v[92:95], off nt
	global_store_dwordx4 v[96:97], v[88:91], off offset:16 nt
	s_nop 1
	s_waitcnt vmcnt(10)
	v_lshlrev_b32_e32 v88, 16, v222
	v_and_b32_e32 v89, 0xffff0000, v222
	v_pk_add_f32 v[84:85], v[84:85], v[88:89]
	v_lshlrev_b32_e32 v88, 16, v223
	v_and_b32_e32 v89, 0xffff0000, v223
	v_pk_add_f32 v[86:87], v[86:87], v[88:89]
	v_lshlrev_b32_e32 v88, 16, v224
	v_and_b32_e32 v89, 0xffff0000, v224
	v_pk_add_f32 v[76:77], v[76:77], v[88:89]
	v_lshlrev_b32_e32 v88, 16, v225
	v_and_b32_e32 v89, 0xffff0000, v225
	v_pk_add_f32 v[78:79], v[78:79], v[88:89]
	global_store_dwordx4 v[96:97], v[84:87], off offset:512 nt
	global_store_dwordx4 v[96:97], v[76:79], off offset:528 nt
	s_nop 1
	s_waitcnt vmcnt(9)
	v_lshlrev_b32_e32 v76, 16, v164
	v_and_b32_e32 v77, 0xffff0000, v164
	v_pk_add_f32 v[76:77], v[80:81], v[76:77]
	v_lshlrev_b32_e32 v80, 16, v166
	v_and_b32_e32 v81, 0xffff0000, v166
	v_pk_add_f32 v[72:73], v[72:73], v[80:81]
	v_lshlrev_b32_e32 v80, 16, v167
	v_and_b32_e32 v81, 0xffff0000, v167
	v_pk_add_f32 v[74:75], v[74:75], v[80:81]
	v_lshlrev_b64 v[80:81], 12, v[196:197]
	v_lshlrev_b32_e32 v78, 16, v165
	v_and_b32_e32 v79, 0xffff0000, v165
	v_lshl_add_u64 v[80:81], s[76:77], 0, v[80:81]
	v_pk_add_f32 v[78:79], v[82:83], v[78:79]
	v_lshl_add_u64 v[80:81], v[80:81], 0, v[120:121]
	global_store_dwordx4 v[80:81], v[76:79], off nt
	global_store_dwordx4 v[80:81], v[72:75], off offset:16 nt
	s_nop 1
	s_waitcnt vmcnt(8)
	v_lshlrev_b32_e32 v72, 16, v160
	v_and_b32_e32 v73, 0xffff0000, v160
	v_pk_add_f32 v[68:69], v[68:69], v[72:73]
	v_lshlrev_b32_e32 v72, 16, v161
	v_and_b32_e32 v73, 0xffff0000, v161
	v_pk_add_f32 v[70:71], v[70:71], v[72:73]
	v_lshlrev_b32_e32 v72, 16, v162
	v_and_b32_e32 v73, 0xffff0000, v162
	v_pk_add_f32 v[64:65], v[64:65], v[72:73]
	v_lshlrev_b32_e32 v72, 16, v163
	v_and_b32_e32 v73, 0xffff0000, v163
	v_pk_add_f32 v[66:67], v[66:67], v[72:73]
	global_store_dwordx4 v[80:81], v[68:71], off offset:512 nt
	global_store_dwordx4 v[80:81], v[64:67], off offset:528 nt
	s_nop 1
	s_waitcnt vmcnt(7)
	v_lshlrev_b32_e32 v64, 16, v156
	v_and_b32_e32 v65, 0xffff0000, v156
	v_pk_add_f32 v[60:61], v[60:61], v[64:65]
	v_lshlrev_b32_e32 v64, 16, v157
	v_and_b32_e32 v65, 0xffff0000, v157
	v_pk_add_f32 v[62:63], v[62:63], v[64:65]
	v_lshlrev_b32_e32 v64, 16, v158
	v_and_b32_e32 v65, 0xffff0000, v158
	v_pk_add_f32 v[56:57], v[56:57], v[64:65]
	v_lshlrev_b32_e32 v64, 16, v159
	v_and_b32_e32 v65, 0xffff0000, v159
	v_pk_add_f32 v[58:59], v[58:59], v[64:65]
	v_lshlrev_b64 v[64:65], 12, v[194:195]
	v_lshl_add_u64 v[64:65], s[76:77], 0, v[64:65]
	v_lshl_add_u64 v[64:65], v[64:65], 0, v[120:121]
	global_store_dwordx4 v[64:65], v[60:63], off nt
	global_store_dwordx4 v[64:65], v[56:59], off offset:16 nt
	s_nop 1
	s_waitcnt vmcnt(6)
	v_lshlrev_b32_e32 v56, 16, v152
	v_and_b32_e32 v57, 0xffff0000, v152
	v_pk_add_f32 v[52:53], v[52:53], v[56:57]
	v_lshlrev_b32_e32 v56, 16, v153
	v_and_b32_e32 v57, 0xffff0000, v153
	v_pk_add_f32 v[54:55], v[54:55], v[56:57]
	v_lshlrev_b32_e32 v56, 16, v154
	v_and_b32_e32 v57, 0xffff0000, v154
	v_pk_add_f32 v[44:45], v[44:45], v[56:57]
	v_lshlrev_b32_e32 v56, 16, v155
	v_and_b32_e32 v57, 0xffff0000, v155
	v_pk_add_f32 v[46:47], v[46:47], v[56:57]
	global_store_dwordx4 v[64:65], v[52:55], off offset:512 nt
	global_store_dwordx4 v[64:65], v[44:47], off offset:528 nt
	s_nop 1
	s_waitcnt vmcnt(5)
;     __device__ __forceinline__ void operator()(const f32x4 (&acc)[2][2][4][2], const pg8::Unit& u, int wr, int wc, int fr, int fq) const {
;     ...
;         for (int ai = 0; ai < 2; ++ai)
; #pragma unroll
;             for (int m = 0; m < 4; ++m) {
;                 const int row = u.pm * 256 + ai * 128 + wr * 64 + m * 16 + fr;
; #pragma unroll
;                 for (int bj = 0; bj < 2; ++bj) {
;                     const size_t off = (size_t)row * DM + u.pn * 256 + 128 * bj + 32 * wc + 8 * fq;
;                     const u32x4 w = xr[ai][m][bj];
;                     f32x4 ya = acc[ai][bj][m][0], yb = acc[ai][bj][m][1];
;                     ya.x += __uint_as_float(w.x << 16); ya.y += __uint_as_float(w.x & 0xffff0000u); ya.z += __uint_as_float(w.y << 16); ya.w += __uint_as_float(w.y & 0xffff0000u);
;                     yb.x += __uint_as_float(w.z << 16); yb.y += __uint_as_float(w.z & 0xffff0000u); yb.z += __uint_as_float(w.w << 16); yb.w += __uint_as_float(w.w & 0xffff0000u);
;                     *(f32x4*)(out + off) = ya; *(f32x4*)(out + off + 4) = yb;
;                 }
	v_lshlrev_b32_e32 v44, 16, v148
	v_and_b32_e32 v45, 0xffff0000, v148
	v_pk_add_f32 v[44:45], v[48:49], v[44:45]
	v_lshlrev_b32_e32 v48, 16, v150
	v_and_b32_e32 v49, 0xffff0000, v150
	v_pk_add_f32 v[40:41], v[40:41], v[48:49]
	v_lshlrev_b32_e32 v48, 16, v151
	v_and_b32_e32 v49, 0xffff0000, v151
	v_pk_add_f32 v[42:43], v[42:43], v[48:49]
	v_lshlrev_b64 v[48:49], 12, v[192:193]
	v_lshlrev_b32_e32 v46, 16, v149
	v_and_b32_e32 v47, 0xffff0000, v149
	v_lshl_add_u64 v[48:49], s[76:77], 0, v[48:49]
	v_pk_add_f32 v[46:47], v[50:51], v[46:47]
	v_lshl_add_u64 v[48:49], v[48:49], 0, v[120:121]
	global_store_dwordx4 v[48:49], v[44:47], off nt
	global_store_dwordx4 v[48:49], v[40:43], off offset:16 nt
	s_nop 1
	s_waitcnt vmcnt(4)
	v_lshlrev_b32_e32 v40, 16, v144
	v_and_b32_e32 v41, 0xffff0000, v144
	v_pk_add_f32 v[36:37], v[36:37], v[40:41]
	v_lshlrev_b32_e32 v40, 16, v145
	v_and_b32_e32 v41, 0xffff0000, v145
	v_pk_add_f32 v[38:39], v[38:39], v[40:41]
	v_lshlrev_b32_e32 v40, 16, v146
	v_and_b32_e32 v41, 0xffff0000, v146
	v_pk_add_f32 v[28:29], v[28:29], v[40:41]
	v_lshlrev_b32_e32 v40, 16, v147
	v_and_b32_e32 v41, 0xffff0000, v147
	v_pk_add_f32 v[30:31], v[30:31], v[40:41]
	global_store_dwordx4 v[48:49], v[36:39], off offset:512 nt
	global_store_dwordx4 v[48:49], v[28:31], off offset:528 nt
	s_nop 1
	s_waitcnt vmcnt(3)
	v_lshlrev_b32_e32 v28, 16, v140
	v_and_b32_e32 v29, 0xffff0000, v140
	v_pk_add_f32 v[28:29], v[32:33], v[28:29]
	v_lshlrev_b32_e32 v32, 16, v142
	v_and_b32_e32 v33, 0xffff0000, v142
	v_pk_add_f32 v[24:25], v[24:25], v[32:33]
	v_lshlrev_b32_e32 v32, 16, v143
	v_and_b32_e32 v33, 0xffff0000, v143
	v_pk_add_f32 v[26:27], v[26:27], v[32:33]
	v_lshlrev_b64 v[32:33], 12, v[190:191]
	v_lshlrev_b32_e32 v30, 16, v141
	v_and_b32_e32 v31, 0xffff0000, v141
	v_lshl_add_u64 v[32:33], s[76:77], 0, v[32:33]
	v_pk_add_f32 v[30:31], v[34:35], v[30:31]
	v_lshl_add_u64 v[32:33], v[32:33], 0, v[120:121]
	global_store_dwordx4 v[32:33], v[28:31], off nt
	global_store_dwordx4 v[32:33], v[24:27], off offset:16 nt
	s_nop 1
	s_waitcnt vmcnt(2)
	v_lshlrev_b32_e32 v24, 16, v136
	v_and_b32_e32 v25, 0xffff0000, v136
	v_pk_add_f32 v[20:21], v[20:21], v[24:25]
	v_lshlrev_b32_e32 v24, 16, v137
	v_and_b32_e32 v25, 0xffff0000, v137
	v_pk_add_f32 v[22:23], v[22:23], v[24:25]
	v_lshlrev_b32_e32 v24, 16, v138
	v_and_b32_e32 v25, 0xffff0000, v138
	v_pk_add_f32 v[12:13], v[12:13], v[24:25]
	v_lshlrev_b32_e32 v24, 16, v139
	v_and_b32_e32 v25, 0xffff0000, v139
	v_pk_add_f32 v[14:15], v[14:15], v[24:25]
	global_store_dwordx4 v[32:33], v[20:23], off offset:512 nt
	global_store_dwordx4 v[32:33], v[12:15], off offset:528 nt
	s_nop 1
	s_waitcnt vmcnt(1)
	v_lshlrev_b32_e32 v12, 16, v132
	v_and_b32_e32 v13, 0xffff0000, v132
	v_pk_add_f32 v[12:13], v[16:17], v[12:13]
	v_lshlrev_b32_e32 v16, 16, v134
	v_and_b32_e32 v17, 0xffff0000, v134
	v_pk_add_f32 v[8:9], v[8:9], v[16:17]
	v_lshlrev_b32_e32 v16, 16, v135
	v_and_b32_e32 v17, 0xffff0000, v135
	v_pk_add_f32 v[10:11], v[10:11], v[16:17]
	v_lshlrev_b64 v[16:17], 12, v[188:189]
	v_lshlrev_b32_e32 v14, 16, v133
	v_and_b32_e32 v15, 0xffff0000, v133
	v_lshl_add_u64 v[16:17], s[76:77], 0, v[16:17]
	v_pk_add_f32 v[14:15], v[18:19], v[14:15]
	v_lshl_add_u64 v[16:17], v[16:17], 0, v[120:121]
	global_store_dwordx4 v[16:17], v[12:15], off nt
	global_store_dwordx4 v[16:17], v[8:11], off offset:16 nt
	s_nop 1
	s_waitcnt vmcnt(0)
	v_lshlrev_b32_e32 v8, 16, v128
	v_and_b32_e32 v9, 0xffff0000, v128
	v_pk_add_f32 v[4:5], v[4:5], v[8:9]
	v_lshlrev_b32_e32 v8, 16, v129
	v_and_b32_e32 v9, 0xffff0000, v129
	v_pk_add_f32 v[6:7], v[6:7], v[8:9]
	v_lshlrev_b32_e32 v8, 16, v130
	v_and_b32_e32 v9, 0xffff0000, v130
	v_pk_add_f32 v[0:1], v[0:1], v[8:9]
	v_lshlrev_b32_e32 v8, 16, v131
	v_and_b32_e32 v9, 0xffff0000, v131
	v_pk_add_f32 v[2:3], v[2:3], v[8:9]
	global_store_dwordx4 v[16:17], v[4:7], off offset:512 nt
	global_store_dwordx4 v[16:17], v[0:3], off offset:528 nt
	s_cbranch_vccnz .LBB0_1053
	s_andn2_b64 vcc, exec, s[2:3]
	s_cbranch_vccnz .LBB0_1052
	s_barrier
	s_branch .LBB0_1052
